# v28 plus 4-byte code shift of the phase-G region (alignment; 15 compensating nops in the following seam)
# speedup vs baseline: 1.0047x; 1.0047x over previous
.LBB0_1224:
	s_nop 0
	s_mov_b64 s[12:13], s[0:1]
	s_getreg_b32 s8, hwreg(HW_REG_XCC_ID, 0, 4)
	s_waitcnt vmcnt(0)
	s_barrier
	s_mov_b64 s[10:11], exec
	v_readlane_b32 s14, v253, 2
	v_readlane_b32 s15, v253, 3
	s_and_b64 s[14:15], s[10:11], s[14:15]
	s_xor_b64 s[10:11], s[14:15], s[10:11]
	s_mov_b64 exec, s[14:15]
	s_cbranch_execz .LBB0_1277
	s_load_dword s9, s[12:13], 0xd8
	s_nop 0
	s_load_dwordx2 s[12:13], s[12:13], 0xc8
	v_readlane_b32 s14, v254, 38
	s_waitcnt vmcnt(0) expcnt(0) lgkmcnt(0)
	s_nop 0
	v_mov_b32_e32 v1, s14
	s_mul_i32 s14, s9, 0xd80
	s_ashr_i32 s15, s14, 31
	s_lshl_b64 s[14:15], s[14:15], 2
	s_add_u32 s9, s12, s14
	s_addc_u32 s13, s13, s15
	ds_read_b32 v3, v1
	s_add_u32 s12, s9, 0x4000
	v_readlane_b32 s9, v254, 39
	s_addc_u32 s13, s13, 0
	s_and_b32 s8, s8, 15
	v_mov_b32_e32 v1, s9
	ds_read_b32 v2, v1
	s_waitcnt lgkmcnt(1)
	v_cmp_ne_u32_e32 vcc, 0, v3
	s_cbranch_vccnz .LBB0_1240
	v_readlane_b32 s14, v253, 0
	v_readlane_b32 s15, v253, 1
	s_load_dwordx2 s[18:19], s[14:15], 0x4
	s_add_u32 s14, s12, 0x1000
	s_addc_u32 s15, s13, 0
	s_add_u32 s16, s12, 0x1100
	s_addc_u32 s17, s13, 0
	s_waitcnt lgkmcnt(0)
	s_mul_i32 s9, s18, s42
	s_add_u32 s18, s12, 0x1200
	s_mul_i32 s9, s9, s19
	s_addc_u32 s19, s13, 0
	s_add_u32 s20, s12, 0x1300
	s_addc_u32 s21, s13, 0
	s_mov_b32 s26, 1
	s_branch .LBB0_1228

.LBB0_1532:
	s_nop 0
	s_nop 0
	s_nop 0
	s_nop 0
	s_nop 0
	s_nop 0
	s_nop 0
	s_nop 0
	s_nop 0
	s_nop 0
	s_nop 0
	s_nop 0
	s_nop 0
	s_nop 0
	s_nop 0
	s_mov_b64 s[12:13], s[0:1]
	s_getreg_b32 s8, hwreg(HW_REG_XCC_ID, 0, 4)
	s_waitcnt vmcnt(0)
	s_barrier
	s_mov_b64 s[10:11], exec
	v_readlane_b32 s14, v253, 2
	v_readlane_b32 s15, v253, 3
	s_and_b64 s[14:15], s[10:11], s[14:15]
	s_xor_b64 s[10:11], s[14:15], s[10:11]
	s_mov_b64 exec, s[14:15]
	s_cbranch_execz .LBB0_1585
	s_load_dword s9, s[12:13], 0xd8
	s_nop 0
	s_load_dwordx2 s[12:13], s[12:13], 0xc8
	v_readlane_b32 s14, v254, 38
	s_waitcnt vmcnt(0) expcnt(0) lgkmcnt(0)
	s_nop 0
	v_mov_b32_e32 v1, s14
	s_mul_i32 s14, s9, 0xd80
	s_ashr_i32 s15, s14, 31
	s_lshl_b64 s[14:15], s[14:15], 2
	s_add_u32 s9, s12, s14
	s_addc_u32 s13, s13, s15
	ds_read_b32 v3, v1
	s_add_u32 s12, s9, 0x4000
	v_readlane_b32 s9, v254, 39
	s_addc_u32 s13, s13, 0
	s_and_b32 s8, s8, 15
	v_mov_b32_e32 v1, s9
	ds_read_b32 v2, v1
	s_waitcnt lgkmcnt(1)
	v_cmp_ne_u32_e32 vcc, 0, v3
	s_cbranch_vccnz .LBB0_1548
	v_readlane_b32 s14, v253, 0
	v_readlane_b32 s15, v253, 1
	s_load_dwordx2 s[18:19], s[14:15], 0x4
	s_add_u32 s14, s12, 0x1000
	s_addc_u32 s15, s13, 0
	s_add_u32 s16, s12, 0x1100
	s_addc_u32 s17, s13, 0
	s_waitcnt lgkmcnt(0)
	s_mul_i32 s9, s18, s42
	s_add_u32 s18, s12, 0x1200
	s_mul_i32 s9, s9, s19
	s_addc_u32 s19, s13, 0
	s_add_u32 s20, s12, 0x1300
	s_addc_u32 s21, s13, 0
	s_mov_b32 s26, 1
	s_branch .LBB0_1536
